# adds: LRU scan phase raises priority of the two waves that run two units per tile (critical path), reset after the phase
# speedup vs baseline: 1.0230x; 1.0027x over previous
; #define LAS __attribute__((address_space(3)))
; DI float bf1(unsigned short h) { return __uint_as_float(((unsigned)h) << 16); }
; DI float frcp(float x) { return __builtin_amdgcn_rcpf(x); }
; DI void lru_unit_run(LruUnit& U, const bf16x8 (&wr)[3], const bf16x8 (&wi)[3], LAS unsigned char* xcb, LAS unsigned char* hst, int cb, int lane) {
;     const int c = lane & 15, q = lane >> 4;
;     float hc = U.hc;
; #pragma unroll 1
;     for (int half = 0; half < 2; ++half) {
;         float av[4][4], bv[4][4], Ac[4], Bc[4];
; #pragma unroll
;         for (int t = 0; t < 4; ++t) {
;             const int tb = 4 * half + t;
;             f32x4 ar = {0.f, 0.f, 0.f, 0.f}, ai = {0.f, 0.f, 0.f, 0.f};
; #pragma unroll
;             for (int ks = 0; ks < 3; ++ks) {
;                 const bf16x8 a = *(const LAS bf16x8*)(xcb + (16 * tb + c) * 192 + (32 * ks + 8 * q) * 2);
;                 ar = __builtin_amdgcn_mfma_f32_16x16x32_bf16(a, wr[ks], ar, 0, 0, 0);
;                 ai = __builtin_amdgcn_mfma_f32_16x16x32_bf16(a, wi[ks], ai, 0, 0, 0);
;             }
; #pragma unroll
;             for (int e = 0; e < 4; ++e) {
;                 const int s = 16 * tb + 4 * q + e;
;                 const float xc = bf1(*(const LAS unsigned short*)(xcb + s * 192 + (16 * cb + c) * 2));
;                 const float r = frcp(1.0f + __builtin_amdgcn_exp2f(-(ar[e] + U.ba))), ig = frcp(1.0f + __builtin_amdgcn_exp2f(-(ai[e] + U.bx)));
;                 const float a = __builtin_amdgcn_exp2f(U.kk * r);
;                 av[t][e] = a; bv[t][e] = __builtin_amdgcn_sqrtf(fmaxf(1.0f - a * a, 0.f)) * ig * xc;
;             }
;             Ac[t] = av[t][0] * av[t][1] * av[t][2] * av[t][3];
;             Bc[t] = ((bv[t][0] * av[t][1] + bv[t][1]) * av[t][2] + bv[t][2]) * av[t][3] + bv[t][3];
;         }
.LBB0_578:
	v_add_u32_e32 v118, -16, v194
	v_and_b32_e32 v119, 64, v194
	v_cmp_lt_i32_e32 vcc, v118, v119
	s_mov_b32 s1, 0
	s_mov_b64 s[20:21], -1
	v_cndmask_b32_e32 v118, v118, v194, vcc
	v_lshlrev_b32_e32 v223, 2, v118
	v_subrev_u32_e32 v118, 32, v194
	v_cmp_lt_i32_e32 vcc, v118, v119
	s_nop 1
	v_cndmask_b32_e32 v118, v118, v194, vcc
	v_lshlrev_b32_e32 v224, 2, v118
	v_or_b32_e32 v118, v119, v150
	v_mov_b32_e32 v119, 0xc0
	v_lshl_or_b32 v225, v118, 2, v119
	s_cmp_lg_u64 s[24:25], 0
	s_cbranch_scc0 .Llru_prio_skip
	s_setprio 3
.Llru_prio_skip:
.LBB0_579:
	v_or_b32_e32 v118, s1, v200
	v_mad_u32_u24 v130, v118, s93, v203
	ds_read_b128 v[118:121], v130 offset:41984
	ds_read_b128 v[126:129], v130 offset:42048
	v_or_b32_e32 v226, s1, v204
	s_or_b32 s2, s1, 16
	s_and_b64 vcc, exec, s[20:21]
	s_mov_b64 s[20:21], 0
	s_waitcnt lgkmcnt(1)
	v_mfma_f32_16x16x32_bf16 v[122:125], v[118:121], v[2:5], 0
	s_nop 0
	v_mfma_f32_16x16x32_bf16 v[118:121], v[118:121], v[6:9], 0
	s_waitcnt lgkmcnt(0)
	v_mfma_f32_16x16x32_bf16 v[122:125], v[126:129], v[18:21], v[122:125]
	s_nop 0
	v_mfma_f32_16x16x32_bf16 v[118:121], v[126:129], v[22:25], v[118:121]
	ds_read_b128 v[126:129], v130 offset:42112
	s_waitcnt lgkmcnt(0)
	v_mfma_f32_16x16x32_bf16 v[122:125], v[126:129], v[34:37], v[122:125]
	s_nop 0
	v_mfma_f32_16x16x32_bf16 v[128:131], v[126:129], v[38:41], v[118:121]
	s_nop 2
	v_mad_u32_u24 v119, v226, s93, v205
	ds_read_u16 v146, v119 offset:41984
	ds_read_u16 v147, v119 offset:42176
	ds_read_u16 v148, v119 offset:42368
	ds_read_u16 v149, v119 offset:42560
	v_add_f32_e32 v119, v186, v125
	v_exp_f32_e64 v119, -v119
	v_add_f32_e32 v121, v220, v129
	v_exp_f32_e64 v121, -v121
	v_add_f32_e32 v120, v220, v128
	v_add_f32_e32 v119, 1.0, v119
	v_rcp_f32_e32 v119, v119
	v_add_f32_e32 v121, 1.0, v121
	v_rcp_f32_e32 v128, v121
	v_add_f32_e32 v121, v186, v124
	v_mul_f32_e32 v119, v187, v119
	v_exp_f32_e32 v124, v119
	v_or_b32_e32 v119, s2, v200
	v_mad_u32_u24 v119, v119, s93, v203
	ds_read_b128 v[134:137], v119 offset:41984
	ds_read_b128 v[142:145], v119 offset:42048
	s_waitcnt lgkmcnt(1)
	v_mfma_f32_16x16x32_bf16 v[138:141], v[134:137], v[2:5], 0
	v_exp_f32_e64 v121, -v121
	v_add_f32_e32 v118, v186, v122
	v_add_f32_e32 v122, v220, v130
	v_mfma_f32_16x16x32_bf16 v[134:137], v[134:137], v[6:9], 0
	v_add_f32_e32 v121, 1.0, v121
	v_rcp_f32_e32 v121, v121
	v_exp_f32_e64 v122, -v122
	s_waitcnt lgkmcnt(0)
	v_mfma_f32_16x16x32_bf16 v[138:141], v[142:145], v[18:21], v[138:141]
	v_exp_f32_e64 v120, -v120
	v_mul_f32_e32 v121, v187, v121
	v_add_f32_e32 v122, 1.0, v122
	v_mfma_f32_16x16x32_bf16 v[134:137], v[142:145], v[22:25], v[134:137]
	ds_read_b128 v[142:145], v119 offset:42112
	v_rcp_f32_e32 v130, v122
	v_exp_f32_e32 v122, v121
	v_add_f32_e32 v121, v220, v131
	v_exp_f32_e64 v121, -v121
	s_waitcnt lgkmcnt(0)
	v_mfma_f32_16x16x32_bf16 v[138:141], v[142:145], v[34:37], v[138:141]
	v_exp_f32_e64 v118, -v118
	v_or_b32_e32 v119, s2, v204
	v_add_f32_e32 v121, 1.0, v121
	v_mfma_f32_16x16x32_bf16 v[134:137], v[142:145], v[38:41], v[134:137]
	v_mad_u32_u24 v125, v119, s93, v205
	s_nop 2
	v_add_f32_e32 v119, v186, v138
	v_rcp_f32_e32 v132, v121
	v_exp_f32_e64 v119, -v119
	v_add_f32_e32 v120, 1.0, v120
	v_add_f32_e32 v121, v220, v134
	v_exp_f32_e64 v121, -v121
	v_add_f32_e32 v118, 1.0, v118
	v_rcp_f32_e32 v126, v120
	v_add_f32_e32 v120, v186, v123
	v_add_f32_e32 v123, v220, v135
	v_rcp_f32_e32 v118, v118
	v_exp_f32_e64 v123, -v123
	v_add_f32_e32 v119, 1.0, v119
	v_rcp_f32_e32 v119, v119
	v_add_f32_e32 v121, 1.0, v121
	v_rcp_f32_e32 v127, v121
	v_add_f32_e32 v121, v186, v139
	v_mul_f32_e32 v118, v187, v118
	v_exp_f32_e64 v120, -v120
	ds_read_u16 v142, v125 offset:41984
	ds_read_u16 v134, v125 offset:42176
	ds_read_u16 v135, v125 offset:42368
	ds_read_u16 v143, v125 offset:42560
	v_exp_f32_e64 v121, -v121
	v_add_f32_e32 v123, 1.0, v123
	v_exp_f32_e32 v118, v118
	v_rcp_f32_e32 v129, v123
	v_add_f32_e32 v123, v186, v140
	v_mul_f32_e32 v119, v187, v119
	v_exp_f32_e64 v123, -v123
	v_exp_f32_e32 v119, v119
	v_add_f32_e32 v125, v186, v141
	v_add_f32_e32 v120, 1.0, v120
	v_add_f32_e32 v121, 1.0, v121
	v_exp_f32_e64 v125, -v125
	v_rcp_f32_e32 v120, v120
	v_rcp_f32_e32 v121, v121
	s_waitcnt lgkmcnt(2)
	v_lshlrev_b32_e32 v139, 16, v134
	v_fma_f32 v134, -v118, v118, 1.0
	v_add_f32_e32 v123, 1.0, v123
	v_max_f32_e32 v134, 0, v134
	v_rcp_f32_e32 v123, v123
	v_sqrt_f32_e32 v144, v134
	v_fma_f32 v134, -v119, v119, 1.0
	v_add_f32_e32 v125, 1.0, v125
	v_max_f32_e32 v134, 0, v134
	v_mul_f32_e32 v120, v187, v120
	v_mul_f32_e32 v121, v187, v121
	v_rcp_f32_e32 v125, v125
	v_sqrt_f32_e32 v145, v134
	v_exp_f32_e32 v120, v120
	v_exp_f32_e32 v121, v121
	v_mul_f32_e32 v123, v187, v123
	v_exp_f32_e32 v123, v123
	v_add_f32_e32 v131, v220, v136
	v_add_f32_e32 v133, v220, v137
	v_mul_f32_e32 v125, v187, v125
	v_lshlrev_b32_e32 v136, 16, v146
	v_lshlrev_b32_e32 v137, 16, v142
	v_pk_mul_f32 v[126:127], v[126:127], v[144:145]
	v_exp_f32_e32 v125, v125
	v_fma_f32 v134, -v120, v120, 1.0
	v_pk_mul_f32 v[126:127], v[126:127], v[136:137]
	v_fma_f32 v136, -v121, v121, 1.0
	v_exp_f32_e64 v131, -v131
	v_exp_f32_e64 v133, -v133
	v_max_f32_e32 v134, 0, v134
	v_max_f32_e32 v136, 0, v136
	v_lshlrev_b32_e32 v138, 16, v147
	v_sqrt_f32_e32 v146, v134
	v_fma_f32 v134, -v122, v122, 1.0
	v_sqrt_f32_e32 v147, v136
	v_fma_f32 v136, -v123, v123, 1.0
	v_max_f32_e32 v134, 0, v134
	v_max_f32_e32 v136, 0, v136
	v_lshlrev_b32_e32 v140, 16, v148
	v_lshlrev_b32_e32 v142, 16, v149
	v_sqrt_f32_e32 v148, v134
	v_fma_f32 v134, -v124, v124, 1.0
	v_sqrt_f32_e32 v149, v136
	v_fma_f32 v136, -v125, v125, 1.0
	v_add_f32_e32 v131, 1.0, v131
	v_add_f32_e32 v133, 1.0, v133
	v_max_f32_e32 v134, 0, v134
	v_max_f32_e32 v136, 0, v136
	v_rcp_f32_e32 v131, v131
	v_rcp_f32_e32 v133, v133
	v_sqrt_f32_e32 v182, v134
	v_sqrt_f32_e32 v183, v136
	v_pk_mul_f32 v[128:129], v[128:129], v[146:147]
	s_or_b32 s2, s1, 32
	v_pk_mul_f32 v[128:129], v[128:129], v[138:139]
	v_or_b32_e32 v138, s2, v200
	s_waitcnt lgkmcnt(1)
; #define LAS __attribute__((address_space(3)))
; DI float bf1(unsigned short h) { return __uint_as_float(((unsigned)h) << 16); }
; DI float frcp(float x) { return __builtin_amdgcn_rcpf(x); }
; DI void lru_unit_run(LruUnit& U, const bf16x8 (&wr)[3], const bf16x8 (&wi)[3], LAS unsigned char* xcb, LAS unsigned char* hst, int cb, int lane) {
;     ...
;         for (int t = 0; t < 4; ++t) {
;             const int tb = 4 * half + t;
;             f32x4 ar = {0.f, 0.f, 0.f, 0.f}, ai = {0.f, 0.f, 0.f, 0.f};
; #pragma unroll
;             for (int ks = 0; ks < 3; ++ks) {
;                 const bf16x8 a = *(const LAS bf16x8*)(xcb + (16 * tb + c) * 192 + (32 * ks + 8 * q) * 2);
;                 ar = __builtin_amdgcn_mfma_f32_16x16x32_bf16(a, wr[ks], ar, 0, 0, 0);
;                 ai = __builtin_amdgcn_mfma_f32_16x16x32_bf16(a, wi[ks], ai, 0, 0, 0);
;             }
; #pragma unroll
;             for (int e = 0; e < 4; ++e) {
;                 const int s = 16 * tb + 4 * q + e;
;                 const float xc = bf1(*(const LAS unsigned short*)(xcb + s * 192 + (16 * cb + c) * 2));
;                 const float r = frcp(1.0f + __builtin_amdgcn_exp2f(-(ar[e] + U.ba))), ig = frcp(1.0f + __builtin_amdgcn_exp2f(-(ai[e] + U.bx)));
;                 const float a = __builtin_amdgcn_exp2f(U.kk * r);
;                 av[t][e] = a; bv[t][e] = __builtin_amdgcn_sqrtf(fmaxf(1.0f - a * a, 0.f)) * ig * xc;
;             }
;             Ac[t] = av[t][0] * av[t][1] * av[t][2] * av[t][3];
;             Bc[t] = ((bv[t][0] * av[t][1] + bv[t][1]) * av[t][2] + bv[t][2]) * av[t][3] + bv[t][3];
;         }
	v_lshlrev_b32_e32 v141, 16, v135
	v_pk_mul_f32 v[130:131], v[130:131], v[148:149]
	v_pk_mul_f32 v[132:133], v[132:133], v[182:183]
	v_mad_u32_u24 v182, v138, s93, v203
	v_pk_mul_f32 v[130:131], v[130:131], v[140:141]
	ds_read_b128 v[138:141], v182 offset:41984
	ds_read_b128 v[146:149], v182 offset:42048
	s_waitcnt lgkmcnt(2)
	v_lshlrev_b32_e32 v143, 16, v143
	v_pk_mul_f32 v[132:133], v[132:133], v[142:143]
	s_waitcnt lgkmcnt(1)
	v_mfma_f32_16x16x32_bf16 v[142:145], v[138:141], v[2:5], 0
	s_or_b32 s1, s1, 48
	v_pk_mul_f32 v[134:135], v[118:119], v[120:121]
	v_pk_fma_f32 v[136:137], v[120:121], v[126:127], v[128:129]
	v_mfma_f32_16x16x32_bf16 v[138:141], v[138:141], v[6:9], 0
	v_mul_f32_e64 v134, v122, v134
	v_mul_f32_e64 v135, v123, v135
	v_pk_fma_f32 v[136:137], v[122:123], v[136:137], v[130:131]
	v_pk_mul_f32 v[134:135], v[124:125], v[134:135]
	s_waitcnt lgkmcnt(0)
	v_mfma_f32_16x16x32_bf16 v[142:145], v[146:149], v[18:21], v[142:145]
	v_fma_f32 v136, v124, v136, v132
	v_fma_f32 v137, v125, v137, v133
	v_mfma_f32_16x16x32_bf16 v[138:141], v[146:149], v[22:25], v[138:141]
	ds_read_b128 v[146:149], v182 offset:42112
	s_waitcnt lgkmcnt(0)
	v_mfma_f32_16x16x32_bf16 v[142:145], v[146:149], v[34:37], v[142:145]
	v_mfma_f32_16x16x32_bf16 v[182:185], v[146:149], v[38:41], v[138:141]
	s_nop 3
	v_or_b32_e32 v138, s2, v204
	v_mad_u32_u24 v139, v138, s93, v205
	ds_read_u16 v227, v139 offset:41984
	ds_read_u16 v240, v139 offset:42176
	ds_read_u16 v241, v139 offset:42368
	ds_read_u16 v242, v139 offset:42560
	v_add_f32_e32 v139, v186, v145
	v_exp_f32_e64 v139, -v139
	v_add_f32_e32 v141, v220, v183
	v_exp_f32_e64 v141, -v141
	v_add_f32_e32 v138, v186, v142
	v_add_f32_e32 v139, 1.0, v139
	v_rcp_f32_e32 v139, v139
	v_add_f32_e32 v141, 1.0, v141
	v_rcp_f32_e32 v148, v141
	v_add_f32_e32 v141, v186, v144
	v_mul_f32_e32 v139, v187, v139
	v_exp_f32_e32 v144, v139
	v_or_b32_e32 v139, s1, v200
	v_mad_u32_u24 v139, v139, s93, v203
	ds_read_b128 v[228:231], v139 offset:41984
	ds_read_b128 v[236:239], v139 offset:42048
	s_waitcnt lgkmcnt(1)
	v_mfma_f32_16x16x32_bf16 v[232:235], v[228:231], v[2:5], 0
	v_exp_f32_e64 v141, -v141
	v_add_f32_e32 v142, v220, v184
	v_exp_f32_e64 v142, -v142
	v_mfma_f32_16x16x32_bf16 v[228:231], v[228:231], v[6:9], 0
	v_add_f32_e32 v141, 1.0, v141
	v_rcp_f32_e32 v141, v141
	v_add_f32_e32 v142, 1.0, v142
	s_waitcnt lgkmcnt(0)
	v_mfma_f32_16x16x32_bf16 v[232:235], v[236:239], v[18:21], v[232:235]
	v_add_f32_e32 v140, v220, v182
	v_mul_f32_e32 v141, v187, v141
	v_rcp_f32_e32 v182, v142
	v_mfma_f32_16x16x32_bf16 v[228:231], v[236:239], v[22:25], v[228:231]
	ds_read_b128 v[236:239], v139 offset:42112
	v_exp_f32_e32 v142, v141
	v_add_f32_e32 v141, v220, v185
	s_waitcnt lgkmcnt(0)
	v_mfma_f32_16x16x32_bf16 v[232:235], v[236:239], v[34:37], v[232:235]
	v_exp_f32_e64 v140, -v140
	v_exp_f32_e64 v141, -v141
	v_exp_f32_e64 v138, -v138
	v_mfma_f32_16x16x32_bf16 v[228:231], v[236:239], v[38:41], v[228:231]
	v_or_b32_e32 v139, s1, v204
	v_mad_u32_u24 v145, v139, s93, v205
	s_nop 1
	v_add_f32_e32 v139, v186, v232
	v_add_f32_e32 v140, 1.0, v140
	v_add_f32_e32 v141, 1.0, v141
	v_exp_f32_e64 v139, -v139
	v_rcp_f32_e32 v146, v140
	v_add_f32_e32 v140, v186, v143
	v_rcp_f32_e32 v184, v141
	v_add_f32_e32 v141, v220, v228
	v_add_f32_e32 v138, 1.0, v138
	v_exp_f32_e64 v140, -v140
	v_exp_f32_e64 v141, -v141
	v_rcp_f32_e32 v138, v138
	v_add_f32_e32 v143, v220, v229
	v_add_f32_e32 v139, 1.0, v139
	v_exp_f32_e64 v143, -v143
	v_rcp_f32_e32 v139, v139
	v_add_f32_e32 v140, 1.0, v140
	v_add_f32_e32 v141, 1.0, v141
	v_mul_f32_e32 v138, v187, v138
	v_rcp_f32_e32 v140, v140
	v_rcp_f32_e32 v147, v141
	v_add_f32_e32 v141, v186, v233
	v_exp_f32_e32 v138, v138
	v_exp_f32_e64 v141, -v141
	v_add_f32_e32 v143, 1.0, v143
	ds_read_u16 v236, v145 offset:41984
	ds_read_u16 v232, v145 offset:42176
	ds_read_u16 v233, v145 offset:42368
	v_mul_f32_e32 v139, v187, v139
	v_rcp_f32_e32 v149, v143
	v_add_f32_e32 v143, v186, v234
	v_exp_f32_e32 v139, v139
	v_exp_f32_e64 v143, -v143
	v_mul_f32_e32 v140, v187, v140
	ds_read_u16 v234, v145 offset:42560
	v_add_f32_e32 v145, v186, v235
	v_exp_f32_e32 v140, v140
	v_add_f32_e32 v141, 1.0, v141
	v_exp_f32_e64 v145, -v145
	v_lshlrev_b32_e32 v228, 16, v227
	v_fma_f32 v227, -v138, v138, 1.0
	v_rcp_f32_e32 v141, v141
	v_max_f32_e32 v227, 0, v227
	v_add_f32_e32 v143, 1.0, v143
	s_waitcnt lgkmcnt(3)
	v_lshlrev_b32_e32 v229, 16, v236
	v_sqrt_f32_e32 v236, v227
	v_fma_f32 v227, -v139, v139, 1.0
	v_rcp_f32_e32 v143, v143
	v_max_f32_e32 v227, 0, v227
	v_add_f32_e32 v145, 1.0, v145
	v_sqrt_f32_e32 v237, v227
	v_fma_f32 v227, -v140, v140, 1.0
	v_mul_f32_e32 v141, v187, v141
	v_rcp_f32_e32 v145, v145
	v_max_f32_e32 v227, 0, v227
	v_exp_f32_e32 v141, v141
	v_sqrt_f32_e32 v238, v227
	v_fma_f32 v227, -v142, v142, 1.0
	v_mul_f32_e32 v143, v187, v143
	v_max_f32_e32 v227, 0, v227
	v_add_f32_e32 v183, v220, v230
	v_exp_f32_e32 v143, v143
	v_lshlrev_b32_e32 v230, 16, v240
	v_sqrt_f32_e32 v240, v227
	v_fma_f32 v227, -v144, v144, 1.0
	v_mul_f32_e32 v145, v187, v145
	v_max_f32_e32 v227, 0, v227
	v_exp_f32_e64 v183, -v183
	v_add_f32_e32 v185, v220, v231
	v_exp_f32_e32 v145, v145
	s_waitcnt lgkmcnt(0)
; #define LAS __attribute__((address_space(3)))
; DI unsigned pk2(float lo, float hi) { f32x2_t v = {lo, hi}; bf16x2_t b = __builtin_convertvector(v, bf16x2_t); return __builtin_bit_cast(unsigned, b); }
; DI void lru_unit_run(LruUnit& U, const bf16x8 (&wr)[3], const bf16x8 (&wi)[3], LAS unsigned char* xcb, LAS unsigned char* hst, int cb, int lane) {
;     ...
; #pragma unroll
;         for (int t = 0; t < 4; ++t) { const float A1 = __shfl_up(Ac[t], 16), B1 = __shfl_up(Bc[t], 16); if (q >= 1) { Bc[t] = Ac[t] * B1 + Bc[t]; Ac[t] = A1 * Ac[t]; } }
; #pragma unroll
;         for (int t = 0; t < 4; ++t) { const float A2 = __shfl_up(Ac[t], 32), B2 = __shfl_up(Bc[t], 32); if (q >= 2) { Bc[t] = Ac[t] * B2 + Bc[t]; Ac[t] = A2 * Ac[t]; } }
;         float At[4], Bt[4], Ae[4], Be[4];
; #pragma unroll
;         for (int t = 0; t < 4; ++t) { At[t] = __shfl(Ac[t], 48 + c); Bt[t] = __shfl(Bc[t], 48 + c); Ae[t] = __shfl_up(Ac[t], 16); Be[t] = __shfl_up(Bc[t], 16); }
; #pragma unroll
;         for (int t = 0; t < 4; ++t) {
;             const int tb = 4 * half + t;
;             float h = (q == 0) ? hc : (Ae[t] * hc + Be[t]);
; #pragma unroll
;             for (int e = 0; e < 4; ++e) { h = av[t][e] * h + bv[t][e]; *(LAS unsigned short*)(hst + (16 * tb + 4 * q + e) * 160 + (16 * cb + c) * 2) = (unsigned short)pk2(h, 0.f); }
;             hc = At[t] * hc + Bt[t];
;         }
;     }
	v_lshlrev_b32_e32 v235, 16, v234
	v_lshlrev_b32_e32 v234, 16, v242
	v_sqrt_f32_e32 v242, v227
	v_fma_f32 v227, -v141, v141, 1.0
	v_exp_f32_e64 v185, -v185
	v_max_f32_e32 v227, 0, v227
	v_sqrt_f32_e32 v239, v227
	v_fma_f32 v227, -v143, v143, 1.0
	v_max_f32_e32 v227, 0, v227
	v_add_f32_e32 v183, 1.0, v183
	v_lshlrev_b32_e32 v231, 16, v232
	v_lshlrev_b32_e32 v232, 16, v241
	v_sqrt_f32_e32 v241, v227
	v_fma_f32 v227, -v145, v145, 1.0
	v_rcp_f32_e32 v183, v183
	v_add_f32_e32 v185, 1.0, v185
	v_max_f32_e32 v227, 0, v227
	v_rcp_f32_e32 v185, v185
	v_sqrt_f32_e32 v243, v227
	v_lshlrev_b32_e32 v233, 16, v233
	v_pk_mul_f32 v[148:149], v[148:149], v[238:239]
	v_pk_mul_f32 v[182:183], v[182:183], v[240:241]
	v_pk_mul_f32 v[148:149], v[148:149], v[230:231]
	v_pk_mul_f32 v[182:183], v[182:183], v[232:233]
	v_pk_mul_f32 v[184:185], v[184:185], v[242:243]
	v_cndmask_b32_e64 v231, v137, v137, s[16:17]
	v_cndmask_b32_e64 v232, v135, v135, s[16:17]
	v_pk_mul_f32 v[146:147], v[146:147], v[236:237]
	v_pk_mul_f32 v[184:185], v[184:185], v[234:235]
	ds_bpermute_b32 v233, v223, v232
	ds_bpermute_b32 v234, v223, v231
	v_pk_mul_f32 v[146:147], v[146:147], v[228:229]
	v_pk_mul_f32 v[244:245], v[138:139], v[140:141]
	v_pk_fma_f32 v[228:229], v[140:141], v[146:147], v[148:149]
	v_pk_mul_f32 v[244:245], v[142:143], v[244:245]
	v_pk_fma_f32 v[228:229], v[142:143], v[228:229], v[182:183]
	v_pk_mul_f32 v[244:245], v[144:145], v[244:245]
	v_pk_fma_f32 v[228:229], v[144:145], v[228:229], v[184:185]
	ds_bpermute_b32 v227, v223, v134
	ds_bpermute_b32 v230, v223, v136
	s_waitcnt lgkmcnt(2)
	v_fmac_f32_e32 v231, v232, v234
	v_mul_f32_e32 v232, v232, v233
	v_cndmask_b32_e64 v233, v228, v228, s[16:17]
	v_cndmask_b32_e64 v234, v244, v244, s[16:17]
	ds_bpermute_b32 v235, v223, v234
	ds_bpermute_b32 v236, v223, v233
	s_waitcnt lgkmcnt(2)
	v_fma_f32 v230, v134, v230, v136
	v_mul_f32_e32 v227, v134, v227
	v_cndmask_b32_e64 v136, v230, v136, s[16:17]
	v_cndmask_b32_e64 v134, v227, v134, s[16:17]
	s_waitcnt lgkmcnt(0)
	v_fmac_f32_e32 v233, v234, v236
	v_mul_f32_e32 v234, v234, v235
	v_cndmask_b32_e64 v235, v229, v229, s[16:17]
	v_cndmask_b32_e64 v236, v245, v245, s[16:17]
	v_cndmask_b32_e64 v137, v231, v137, s[16:17]
	v_cndmask_b32_e64 v135, v232, v135, s[16:17]
	ds_bpermute_b32 v227, v224, v134
	ds_bpermute_b32 v232, v224, v136
	ds_bpermute_b32 v237, v223, v236
	ds_bpermute_b32 v238, v223, v235
	v_cndmask_b32_e64 v228, v233, v228, s[16:17]
	v_cndmask_b32_e64 v231, v234, v244, s[16:17]
	ds_bpermute_b32 v233, v224, v135
	ds_bpermute_b32 v234, v224, v137
	s_waitcnt lgkmcnt(4)
	v_fma_f32 v232, v134, v232, v136
	v_mul_f32_e32 v227, v134, v227
	s_waitcnt lgkmcnt(2)
	v_fmac_f32_e32 v235, v236, v238
	v_mul_f32_e32 v236, v236, v237
	s_waitcnt lgkmcnt(0)
	v_fma_f32 v234, v135, v234, v137
	v_mul_f32_e32 v233, v135, v233
	v_cndmask_b32_e64 v136, v136, v232, s[18:19]
	v_cndmask_b32_e64 v134, v134, v227, s[18:19]
	v_cndmask_b32_e64 v229, v235, v229, s[16:17]
	v_cndmask_b32_e64 v230, v236, v245, s[16:17]
	ds_bpermute_b32 v235, v224, v231
	ds_bpermute_b32 v236, v224, v228
	v_cndmask_b32_e64 v137, v137, v234, s[18:19]
	v_cndmask_b32_e64 v135, v135, v233, s[18:19]
	ds_bpermute_b32 v227, v225, v134
	ds_bpermute_b32 v232, v225, v136
	ds_bpermute_b32 v134, v223, v134
	ds_bpermute_b32 v136, v223, v136
	ds_bpermute_b32 v233, v225, v135
	ds_bpermute_b32 v234, v225, v137
	ds_bpermute_b32 v135, v223, v135
	ds_bpermute_b32 v137, v223, v137
	s_waitcnt lgkmcnt(8)
	v_fma_f32 v236, v231, v236, v228
	v_mul_f32_e32 v235, v231, v235
	s_waitcnt lgkmcnt(6)
	v_fmac_f32_e32 v232, v1, v227
	ds_bpermute_b32 v237, v224, v230
	ds_bpermute_b32 v238, v224, v229
	v_cndmask_b32_e64 v228, v228, v236, s[18:19]
	v_cndmask_b32_e64 v231, v231, v235, s[18:19]
	s_waitcnt lgkmcnt(6)
	v_fmac_f32_e32 v136, v1, v134
	s_waitcnt lgkmcnt(2)
	v_fmac_f32_e32 v137, v232, v135
	ds_bpermute_b32 v235, v225, v231
	ds_bpermute_b32 v236, v225, v228
	ds_bpermute_b32 v231, v223, v231
	ds_bpermute_b32 v228, v223, v228
	v_cndmask_b32_e64 v134, v136, v1, s[16:17]
	v_cndmask_b32_e64 v1, v137, v232, s[16:17]
	v_fmac_f32_e32 v127, v119, v1
	v_fma_f32 v118, v118, v134, v126
	v_mad_u32_u24 v134, v226, s57, v206
	v_cvt_pk_bf16_f32 v1, v127, s0
	v_fmac_f32_e32 v129, v121, v127
	ds_write_b16 v134, v1 offset:2560
	v_cvt_pk_bf16_f32 v1, v129, s0
	v_fmac_f32_e32 v131, v123, v129
	s_waitcnt lgkmcnt(5)
	v_fma_f32 v238, v230, v238, v229
	v_mul_f32_e32 v237, v230, v237
	v_cvt_pk_bf16_f32 v126, v118, s0
	v_fma_f32 v118, v120, v118, v128
	ds_write_b16 v134, v1 offset:2720
	v_cvt_pk_bf16_f32 v1, v131, s0
	v_fmac_f32_e32 v133, v125, v131
	v_fmac_f32_e32 v234, v232, v233
	v_cndmask_b32_e64 v229, v229, v238, s[18:19]
	v_cndmask_b32_e64 v230, v230, v237, s[18:19]
	v_cvt_pk_bf16_f32 v120, v118, s0
	v_fma_f32 v118, v122, v118, v130
	ds_write_b16 v134, v1 offset:2880
	v_cvt_pk_bf16_f32 v1, v133, s0
	s_waitcnt lgkmcnt(3)
	v_fmac_f32_e32 v228, v234, v231
	ds_bpermute_b32 v237, v225, v230
	ds_bpermute_b32 v238, v225, v229
	ds_bpermute_b32 v230, v223, v230
	ds_bpermute_b32 v229, v223, v229
	ds_write_b16 v134, v120 offset:160
	v_cvt_pk_bf16_f32 v120, v118, s0
	v_fma_f32 v118, v124, v118, v132
	ds_write_b16 v134, v1 offset:3040
	v_cndmask_b32_e64 v1, v228, v234, s[16:17]
	v_cvt_pk_bf16_f32 v118, v118, s0
	v_fma_f32 v1, v138, v1, v146
	ds_write_b16 v134, v118 offset:480
	v_cvt_pk_bf16_f32 v118, v1, s0
	v_fma_f32 v1, v140, v1, v148
	ds_write_b16 v134, v118 offset:5120
	v_cvt_pk_bf16_f32 v118, v1, s0
	v_fma_f32 v1, v142, v1, v182
	ds_write_b16 v134, v118 offset:5280
	v_cvt_pk_bf16_f32 v118, v1, s0
	v_fma_f32 v1, v144, v1, v184
	v_fmac_f32_e32 v236, v234, v235
	v_cvt_pk_bf16_f32 v1, v1, s0
	s_waitcnt lgkmcnt(5)
	v_fmac_f32_e32 v229, v236, v230
	ds_write_b16 v134, v1 offset:5600
	v_cndmask_b32_e64 v1, v229, v236, s[16:17]
	v_fmac_f32_e32 v147, v139, v1
	v_cvt_pk_bf16_f32 v1, v147, s0
	v_fmac_f32_e32 v149, v141, v147
	ds_write_b16 v134, v1 offset:7680
	v_cvt_pk_bf16_f32 v1, v149, s0
	v_fmac_f32_e32 v183, v143, v149
	ds_write_b16 v134, v1 offset:7840
	v_cvt_pk_bf16_f32 v1, v183, s0
	v_fmac_f32_e32 v185, v145, v183
	ds_write_b16 v134, v1 offset:8000
	v_cvt_pk_bf16_f32 v1, v185, s0
	ds_write_b16 v134, v1 offset:8160
	v_mov_b32_e32 v1, v238
	v_fmac_f32_e32 v1, v236, v237
	s_mov_b32 s1, 64
	ds_write_b16 v134, v126
	ds_write_b16 v134, v120 offset:320
	ds_write_b16 v134, v118 offset:5440
	s_cbranch_vccnz .LBB0_579
	s_andn2_b64 vcc, exec, s[24:25]
	s_cbranch_vccnz .LBB0_583
	s_mov_b32 s1, 0
	s_mov_b64 s[20:21], -1

; #define LAS __attribute__((address_space(3)))
; DI int launder_v(int v) { asm volatile("" : "+v"(v)); return v; }
; #define LBAR() do { asm volatile("s_waitcnt lgkmcnt(0)" ::: "memory"); __builtin_amdgcn_s_barrier(); asm volatile("" ::: "memory"); } while (0)
; DI void lru_item(KP A, const bf16* XL, const bf16* GL, bf16* HG, int b, int nb, LAS unsigned char* lds, int tid, int wave, int lane) {
;     ...
;         LBAR();
;         const int dt2 = launder_v(dtid);
; #pragma unroll
;         for (int i = 0; i < 5; ++i) { const int idx = dt2 + 256 * i; const int srow = idx / 10, c8 = idx % 10; const int t = t0 + (dir ? 127 - srow : srow);
;             v4u hw = *(const LAS v4u*)(hst + srow * 160 + c8 * 16);
.LBB0_583:
	s_setprio 0
	v_mov_b32_e32 v122, v159
	s_waitcnt lgkmcnt(0)
	s_barrier
	v_cndmask_b32_e64 v125, 0, 1, s[84:85]
	v_mul_hi_i32 v118, v122, s51
	v_lshrrev_b32_e32 v119, 31, v118
	v_ashrrev_i32_e32 v118, 2, v118
	v_add_u32_e32 v124, v118, v119
	v_mul_lo_u32 v118, v124, 10
	v_sub_u32_e32 v123, v122, v118
	v_mul_lo_u32 v118, v124, s57
	v_lshlrev_b32_e32 v119, 4, v123
	v_add3_u32 v118, s90, v118, v119
	ds_read_b128 v[118:121], v118
	v_cmp_ne_u32_e64 s[20:21], 1, v125
	s_andn2_b64 vcc, exec, s[84:85]
	s_mov_b64 s[84:85], -1
	s_cbranch_vccnz .LBB0_585
	s_mov_b64 s[84:85], 0
